# nsa_ps_block_regrouped_4_elements
# baseline (speedup 1.0000x reference)
.LBB0_451:
	s_or_b64 exec, exec, s[0:1]
	v_mul_f32_e32 v240, v139, v11
	v_mul_f32_e32 v241, v138, v11
	v_mul_f32_e32 v242, v137, v11
	v_mul_f32_e32 v243, v136, v11
	v_mov_b32_dpp v244, v240 quad_perm:[1,0,3,2] row_mask:0xf bank_mask:0xf
	v_mov_b32_dpp v245, v241 quad_perm:[1,0,3,2] row_mask:0xf bank_mask:0xf
	v_mov_b32_dpp v246, v242 quad_perm:[1,0,3,2] row_mask:0xf bank_mask:0xf
	v_mov_b32_dpp v247, v243 quad_perm:[1,0,3,2] row_mask:0xf bank_mask:0xf
	v_fmac_f32_e32 v244, v139, v11
	v_fmac_f32_e32 v245, v138, v11
	v_fmac_f32_e32 v246, v137, v11
	v_fmac_f32_e32 v247, v136, v11
	v_mov_b32_dpp v248, v244 quad_perm:[2,3,0,1] row_mask:0xf bank_mask:0xf
	v_mov_b32_dpp v249, v245 quad_perm:[2,3,0,1] row_mask:0xf bank_mask:0xf
	v_mov_b32_dpp v250, v246 quad_perm:[2,3,0,1] row_mask:0xf bank_mask:0xf
	v_mov_b32_dpp v251, v247 quad_perm:[2,3,0,1] row_mask:0xf bank_mask:0xf
	v_add_f32_e32 v244, v244, v248
	v_add_f32_e32 v245, v245, v249
	v_add_f32_e32 v246, v246, v250
	v_add_f32_e32 v247, v247, v251
	v_mul_f32_e32 v23, v139, v11
	v_mul_f32_e32 v25, v138, v11
	v_mul_f32_e32 v28, v137, v11
	v_mul_f32_e32 v31, v136, v11
	s_and_saveexec_b64 s[0:1], vcc
	ds_write_b32 v15, v244 offset:12
	ds_write_b32 v15, v245 offset:16
	ds_write_b32 v15, v246 offset:20
	ds_write_b32 v15, v247 offset:24
.LBB0_459:
	s_or_b64 exec, exec, s[0:1]
	v_mul_f32_e32 v240, v135, v11
	v_mul_f32_e32 v241, v134, v11
	v_mul_f32_e32 v242, v133, v11
	v_mul_f32_e32 v243, v132, v11
	v_mov_b32_dpp v244, v240 quad_perm:[1,0,3,2] row_mask:0xf bank_mask:0xf
	v_mov_b32_dpp v245, v241 quad_perm:[1,0,3,2] row_mask:0xf bank_mask:0xf
	v_mov_b32_dpp v246, v242 quad_perm:[1,0,3,2] row_mask:0xf bank_mask:0xf
	v_mov_b32_dpp v247, v243 quad_perm:[1,0,3,2] row_mask:0xf bank_mask:0xf
	v_fmac_f32_e32 v244, v135, v11
	v_fmac_f32_e32 v245, v134, v11
	v_fmac_f32_e32 v246, v133, v11
	v_fmac_f32_e32 v247, v132, v11
	v_mov_b32_dpp v248, v244 quad_perm:[2,3,0,1] row_mask:0xf bank_mask:0xf
	v_mov_b32_dpp v249, v245 quad_perm:[2,3,0,1] row_mask:0xf bank_mask:0xf
	v_mov_b32_dpp v250, v246 quad_perm:[2,3,0,1] row_mask:0xf bank_mask:0xf
	v_mov_b32_dpp v251, v247 quad_perm:[2,3,0,1] row_mask:0xf bank_mask:0xf
	v_add_f32_e32 v244, v244, v248
	v_add_f32_e32 v245, v245, v249
	v_add_f32_e32 v246, v246, v250
	v_add_f32_e32 v247, v247, v251
	v_mul_f32_e32 v33, v135, v11
	v_mul_f32_e32 v32, v134, v11
	v_mul_f32_e32 v34, v133, v11
	v_mul_f32_e32 v35, v132, v11
	s_and_saveexec_b64 s[0:1], vcc
	ds_write_b32 v15, v244 offset:28
	ds_write_b32 v15, v245 offset:128
	ds_write_b32 v15, v246 offset:132
	ds_write_b32 v15, v247 offset:136
.LBB0_467:
	s_or_b64 exec, exec, s[0:1]
	v_mul_f32_e32 v240, v131, v11
	v_mul_f32_e32 v241, v130, v11
	v_mul_f32_e32 v242, v129, v11
	v_mul_f32_e32 v243, v128, v11
	v_mov_b32_dpp v244, v240 quad_perm:[1,0,3,2] row_mask:0xf bank_mask:0xf
	v_mov_b32_dpp v245, v241 quad_perm:[1,0,3,2] row_mask:0xf bank_mask:0xf
	v_mov_b32_dpp v246, v242 quad_perm:[1,0,3,2] row_mask:0xf bank_mask:0xf
	v_mov_b32_dpp v247, v243 quad_perm:[1,0,3,2] row_mask:0xf bank_mask:0xf
	v_fmac_f32_e32 v244, v131, v11
	v_fmac_f32_e32 v245, v130, v11
	v_fmac_f32_e32 v246, v129, v11
	v_fmac_f32_e32 v247, v128, v11
	v_mov_b32_dpp v248, v244 quad_perm:[2,3,0,1] row_mask:0xf bank_mask:0xf
	v_mov_b32_dpp v249, v245 quad_perm:[2,3,0,1] row_mask:0xf bank_mask:0xf
	v_mov_b32_dpp v250, v246 quad_perm:[2,3,0,1] row_mask:0xf bank_mask:0xf
	v_mov_b32_dpp v251, v247 quad_perm:[2,3,0,1] row_mask:0xf bank_mask:0xf
	v_add_f32_e32 v244, v244, v248
	v_add_f32_e32 v245, v245, v249
	v_add_f32_e32 v246, v246, v250
	v_add_f32_e32 v247, v247, v251
	v_mul_f32_e32 v42, v131, v11
	v_mul_f32_e32 v44, v130, v11
	v_mul_f32_e32 v45, v129, v11
	v_mul_f32_e32 v46, v128, v11
	s_and_saveexec_b64 s[0:1], vcc
	ds_write_b32 v15, v244 offset:140
	ds_write_b32 v15, v245 offset:144
	ds_write_b32 v15, v246 offset:148
	ds_write_b32 v15, v247 offset:152

.LBB0_479:
	s_or_b64 exec, exec, s[0:1]
	v_mul_f32_e32 v240, v62, v11
	v_mul_f32_e32 v241, v126, v11
	v_mul_f32_e32 v242, v71, v11
	v_mul_f32_e32 v243, v67, v11
	v_mov_b32_dpp v244, v240 quad_perm:[1,0,3,2] row_mask:0xf bank_mask:0xf
	v_mov_b32_dpp v245, v241 quad_perm:[1,0,3,2] row_mask:0xf bank_mask:0xf
	v_mov_b32_dpp v246, v242 quad_perm:[1,0,3,2] row_mask:0xf bank_mask:0xf
	v_mov_b32_dpp v247, v243 quad_perm:[1,0,3,2] row_mask:0xf bank_mask:0xf
	v_fmac_f32_e32 v244, v62, v11
	v_fmac_f32_e32 v245, v126, v11
	v_fmac_f32_e32 v246, v71, v11
	v_fmac_f32_e32 v247, v67, v11
	v_mov_b32_dpp v248, v244 quad_perm:[2,3,0,1] row_mask:0xf bank_mask:0xf
	v_mov_b32_dpp v249, v245 quad_perm:[2,3,0,1] row_mask:0xf bank_mask:0xf
	v_mov_b32_dpp v250, v246 quad_perm:[2,3,0,1] row_mask:0xf bank_mask:0xf
	v_mov_b32_dpp v251, v247 quad_perm:[2,3,0,1] row_mask:0xf bank_mask:0xf
	v_add_f32_e32 v244, v244, v248
	v_add_f32_e32 v245, v245, v249
	v_add_f32_e32 v246, v246, v250
	v_add_f32_e32 v247, v247, v251
	v_mul_f32_e32 v49, v62, v11
	v_mul_f32_e32 v50, v126, v11
	v_mul_f32_e32 v51, v71, v11
	v_mul_f32_e32 v62, v67, v11
	s_and_saveexec_b64 s[0:1], vcc
	ds_write_b32 v15, v244 offset:260
	ds_write_b32 v15, v245 offset:264
	ds_write_b32 v15, v246 offset:268
	ds_write_b32 v15, v247 offset:272
.LBB0_487:
	s_or_b64 exec, exec, s[0:1]
	v_mul_f32_e32 v240, v127, v11
	v_mul_f32_e32 v241, v125, v11
	v_mul_f32_e32 v242, v70, v11
	v_mul_f32_e32 v243, v123, v11
	v_mov_b32_dpp v244, v240 quad_perm:[1,0,3,2] row_mask:0xf bank_mask:0xf
	v_mov_b32_dpp v245, v241 quad_perm:[1,0,3,2] row_mask:0xf bank_mask:0xf
	v_mov_b32_dpp v246, v242 quad_perm:[1,0,3,2] row_mask:0xf bank_mask:0xf
	v_mov_b32_dpp v247, v243 quad_perm:[1,0,3,2] row_mask:0xf bank_mask:0xf
	v_fmac_f32_e32 v244, v127, v11
	v_fmac_f32_e32 v245, v125, v11
	v_fmac_f32_e32 v246, v70, v11
	v_fmac_f32_e32 v247, v123, v11
	v_mov_b32_dpp v248, v244 quad_perm:[2,3,0,1] row_mask:0xf bank_mask:0xf
	v_mov_b32_dpp v249, v245 quad_perm:[2,3,0,1] row_mask:0xf bank_mask:0xf
	v_mov_b32_dpp v250, v246 quad_perm:[2,3,0,1] row_mask:0xf bank_mask:0xf
	v_mov_b32_dpp v251, v247 quad_perm:[2,3,0,1] row_mask:0xf bank_mask:0xf
	v_add_f32_e32 v244, v244, v248
	v_add_f32_e32 v245, v245, v249
	v_add_f32_e32 v246, v246, v250
	v_add_f32_e32 v247, v247, v251
	v_mul_f32_e32 v65, v127, v11
	v_mul_f32_e32 v67, v125, v11
	v_mul_f32_e32 v71, v70, v11
	v_mul_f32_e32 v70, v123, v11
	s_and_saveexec_b64 s[0:1], vcc
	ds_write_b32 v15, v244 offset:276
	ds_write_b32 v15, v245 offset:280
	ds_write_b32 v15, v246 offset:284
	ds_write_b32 v15, v247 offset:384
.LBB0_495:
	s_or_b64 exec, exec, s[0:1]
	v_mul_f32_e32 v240, v122, v11
	v_mul_f32_e32 v241, v121, v11
	v_mul_f32_e32 v242, v120, v11
	v_mul_f32_e32 v243, v119, v11
	v_mov_b32_dpp v244, v240 quad_perm:[1,0,3,2] row_mask:0xf bank_mask:0xf
	v_mov_b32_dpp v245, v241 quad_perm:[1,0,3,2] row_mask:0xf bank_mask:0xf
	v_mov_b32_dpp v246, v242 quad_perm:[1,0,3,2] row_mask:0xf bank_mask:0xf
	v_mov_b32_dpp v247, v243 quad_perm:[1,0,3,2] row_mask:0xf bank_mask:0xf
	v_fmac_f32_e32 v244, v122, v11
	v_fmac_f32_e32 v245, v121, v11
	v_fmac_f32_e32 v246, v120, v11
	v_fmac_f32_e32 v247, v119, v11
	v_mov_b32_dpp v248, v244 quad_perm:[2,3,0,1] row_mask:0xf bank_mask:0xf
	v_mov_b32_dpp v249, v245 quad_perm:[2,3,0,1] row_mask:0xf bank_mask:0xf
	v_mov_b32_dpp v250, v246 quad_perm:[2,3,0,1] row_mask:0xf bank_mask:0xf
	v_mov_b32_dpp v251, v247 quad_perm:[2,3,0,1] row_mask:0xf bank_mask:0xf
	v_add_f32_e32 v244, v244, v248
	v_add_f32_e32 v245, v245, v249
	v_add_f32_e32 v246, v246, v250
	v_add_f32_e32 v247, v247, v251
	v_mul_f32_e32 v118, v122, v11
	v_mul_f32_e32 v122, v121, v11
	v_mul_f32_e32 v121, v120, v11
	v_mul_f32_e32 v120, v119, v11
	s_and_saveexec_b64 s[0:1], vcc
	ds_write_b32 v15, v244 offset:388
	ds_write_b32 v15, v245 offset:392
	ds_write_b32 v15, v246 offset:396
	ds_write_b32 v15, v247 offset:400

.LBB0_511:
	s_or_b64 exec, exec, s[0:1]
	v_mul_f32_e32 v240, v63, v11
	v_mul_f32_e32 v241, v61, v11
	v_mul_f32_e32 v242, v60, v11
	v_mul_f32_e32 v243, v59, v11
	v_mov_b32_dpp v244, v240 quad_perm:[1,0,3,2] row_mask:0xf bank_mask:0xf
	v_mov_b32_dpp v245, v241 quad_perm:[1,0,3,2] row_mask:0xf bank_mask:0xf
	v_mov_b32_dpp v246, v242 quad_perm:[1,0,3,2] row_mask:0xf bank_mask:0xf
	v_mov_b32_dpp v247, v243 quad_perm:[1,0,3,2] row_mask:0xf bank_mask:0xf
	v_fmac_f32_e32 v244, v63, v11
	v_fmac_f32_e32 v245, v61, v11
	v_fmac_f32_e32 v246, v60, v11
	v_fmac_f32_e32 v247, v59, v11
	v_mov_b32_dpp v248, v244 quad_perm:[2,3,0,1] row_mask:0xf bank_mask:0xf
	v_mov_b32_dpp v249, v245 quad_perm:[2,3,0,1] row_mask:0xf bank_mask:0xf
	v_mov_b32_dpp v250, v246 quad_perm:[2,3,0,1] row_mask:0xf bank_mask:0xf
	v_mov_b32_dpp v251, v247 quad_perm:[2,3,0,1] row_mask:0xf bank_mask:0xf
	v_add_f32_e32 v244, v244, v248
	v_add_f32_e32 v245, v245, v249
	v_add_f32_e32 v246, v246, v250
	v_add_f32_e32 v247, v247, v251
	v_mul_f32_e32 v64, v63, v11
	v_mul_f32_e32 v63, v61, v11
	v_mul_f32_e32 v61, v60, v11
	v_mul_f32_e32 v60, v59, v11
	s_and_saveexec_b64 s[0:1], vcc
	ds_write_b32 v15, v244 offset:516
	ds_write_b32 v15, v245 offset:520
	ds_write_b32 v15, v246 offset:524
	ds_write_b32 v15, v247 offset:528
.LBB0_519:
	s_or_b64 exec, exec, s[0:1]
	v_mul_f32_e32 v240, v58, v11
	v_mul_f32_e32 v241, v57, v11
	v_mul_f32_e32 v242, v56, v11
	v_mul_f32_e32 v243, v55, v11
	v_mov_b32_dpp v244, v240 quad_perm:[1,0,3,2] row_mask:0xf bank_mask:0xf
	v_mov_b32_dpp v245, v241 quad_perm:[1,0,3,2] row_mask:0xf bank_mask:0xf
	v_mov_b32_dpp v246, v242 quad_perm:[1,0,3,2] row_mask:0xf bank_mask:0xf
	v_mov_b32_dpp v247, v243 quad_perm:[1,0,3,2] row_mask:0xf bank_mask:0xf
	v_fmac_f32_e32 v244, v58, v11
	v_fmac_f32_e32 v245, v57, v11
	v_fmac_f32_e32 v246, v56, v11
	v_fmac_f32_e32 v247, v55, v11
	v_mov_b32_dpp v248, v244 quad_perm:[2,3,0,1] row_mask:0xf bank_mask:0xf
	v_mov_b32_dpp v249, v245 quad_perm:[2,3,0,1] row_mask:0xf bank_mask:0xf
	v_mov_b32_dpp v250, v246 quad_perm:[2,3,0,1] row_mask:0xf bank_mask:0xf
	v_mov_b32_dpp v251, v247 quad_perm:[2,3,0,1] row_mask:0xf bank_mask:0xf
	v_add_f32_e32 v244, v244, v248
	v_add_f32_e32 v245, v245, v249
	v_add_f32_e32 v246, v246, v250
	v_add_f32_e32 v247, v247, v251
	v_mul_f32_e32 v59, v58, v11
	v_mul_f32_e32 v58, v57, v11
	v_mul_f32_e32 v57, v56, v11
	v_mul_f32_e32 v56, v55, v11
	s_and_saveexec_b64 s[0:1], vcc
	ds_write_b32 v15, v244 offset:532
	ds_write_b32 v15, v245 offset:536
	ds_write_b32 v15, v246 offset:540
	ds_write_b32 v15, v247 offset:640
.LBB0_527:
	s_or_b64 exec, exec, s[0:1]
	v_mul_f32_e32 v240, v54, v11
	v_mul_f32_e32 v241, v53, v11
	v_mul_f32_e32 v242, v52, v11
	v_mul_f32_e32 v243, v43, v11
	v_mov_b32_dpp v244, v240 quad_perm:[1,0,3,2] row_mask:0xf bank_mask:0xf
	v_mov_b32_dpp v245, v241 quad_perm:[1,0,3,2] row_mask:0xf bank_mask:0xf
	v_mov_b32_dpp v246, v242 quad_perm:[1,0,3,2] row_mask:0xf bank_mask:0xf
	v_mov_b32_dpp v247, v243 quad_perm:[1,0,3,2] row_mask:0xf bank_mask:0xf
	v_fmac_f32_e32 v244, v54, v11
	v_fmac_f32_e32 v245, v53, v11
	v_fmac_f32_e32 v246, v52, v11
	v_fmac_f32_e32 v247, v43, v11
	v_mov_b32_dpp v248, v244 quad_perm:[2,3,0,1] row_mask:0xf bank_mask:0xf
	v_mov_b32_dpp v249, v245 quad_perm:[2,3,0,1] row_mask:0xf bank_mask:0xf
	v_mov_b32_dpp v250, v246 quad_perm:[2,3,0,1] row_mask:0xf bank_mask:0xf
	v_mov_b32_dpp v251, v247 quad_perm:[2,3,0,1] row_mask:0xf bank_mask:0xf
	v_add_f32_e32 v244, v244, v248
	v_add_f32_e32 v245, v245, v249
	v_add_f32_e32 v246, v246, v250
	v_add_f32_e32 v247, v247, v251
	v_mul_f32_e32 v55, v54, v11
	v_mul_f32_e32 v54, v53, v11
	v_mul_f32_e32 v53, v52, v11
	v_mul_f32_e32 v52, v43, v11
	s_and_saveexec_b64 s[0:1], vcc
	ds_write_b32 v15, v244 offset:644
	ds_write_b32 v15, v245 offset:648
	ds_write_b32 v15, v246 offset:652
	ds_write_b32 v15, v247 offset:656

.LBB0_543:
	s_or_b64 exec, exec, s[0:1]
	v_mul_f32_e32 v240, v30, v11
	v_mul_f32_e32 v241, v29, v11
	v_mul_f32_e32 v242, v27, v11
	v_mul_f32_e32 v243, v26, v11
	v_mov_b32_dpp v244, v240 quad_perm:[1,0,3,2] row_mask:0xf bank_mask:0xf
	v_mov_b32_dpp v245, v241 quad_perm:[1,0,3,2] row_mask:0xf bank_mask:0xf
	v_mov_b32_dpp v246, v242 quad_perm:[1,0,3,2] row_mask:0xf bank_mask:0xf
	v_mov_b32_dpp v247, v243 quad_perm:[1,0,3,2] row_mask:0xf bank_mask:0xf
	v_fmac_f32_e32 v244, v30, v11
	v_fmac_f32_e32 v245, v29, v11
	v_fmac_f32_e32 v246, v27, v11
	v_fmac_f32_e32 v247, v26, v11
	v_mov_b32_dpp v248, v244 quad_perm:[2,3,0,1] row_mask:0xf bank_mask:0xf
	v_mov_b32_dpp v249, v245 quad_perm:[2,3,0,1] row_mask:0xf bank_mask:0xf
	v_mov_b32_dpp v250, v246 quad_perm:[2,3,0,1] row_mask:0xf bank_mask:0xf
	v_mov_b32_dpp v251, v247 quad_perm:[2,3,0,1] row_mask:0xf bank_mask:0xf
	v_add_f32_e32 v244, v244, v248
	v_add_f32_e32 v245, v245, v249
	v_add_f32_e32 v246, v246, v250
	v_add_f32_e32 v247, v247, v251
	v_mul_f32_e32 v123, v30, v11
	v_mul_f32_e32 v125, v29, v11
	v_mul_f32_e32 v126, v27, v11
	v_mul_f32_e32 v127, v26, v11
	s_and_saveexec_b64 s[0:1], vcc
	ds_write_b32 v15, v244 offset:772
	ds_write_b32 v15, v245 offset:776
	ds_write_b32 v15, v246 offset:780
	ds_write_b32 v15, v247 offset:784
.LBB0_551:
	s_or_b64 exec, exec, s[0:1]
	v_mul_f32_e32 v240, v24, v11
	v_mul_f32_e32 v241, v22, v11
	v_mul_f32_e32 v242, v21, v11
	v_mul_f32_e32 v243, v20, v11
	v_mov_b32_dpp v244, v240 quad_perm:[1,0,3,2] row_mask:0xf bank_mask:0xf
	v_mov_b32_dpp v245, v241 quad_perm:[1,0,3,2] row_mask:0xf bank_mask:0xf
	v_mov_b32_dpp v246, v242 quad_perm:[1,0,3,2] row_mask:0xf bank_mask:0xf
	v_mov_b32_dpp v247, v243 quad_perm:[1,0,3,2] row_mask:0xf bank_mask:0xf
	v_fmac_f32_e32 v244, v24, v11
	v_fmac_f32_e32 v245, v22, v11
	v_fmac_f32_e32 v246, v21, v11
	v_fmac_f32_e32 v247, v20, v11
	v_mov_b32_dpp v248, v244 quad_perm:[2,3,0,1] row_mask:0xf bank_mask:0xf
	v_mov_b32_dpp v249, v245 quad_perm:[2,3,0,1] row_mask:0xf bank_mask:0xf
	v_mov_b32_dpp v250, v246 quad_perm:[2,3,0,1] row_mask:0xf bank_mask:0xf
	v_mov_b32_dpp v251, v247 quad_perm:[2,3,0,1] row_mask:0xf bank_mask:0xf
	v_add_f32_e32 v244, v244, v248
	v_add_f32_e32 v245, v245, v249
	v_add_f32_e32 v246, v246, v250
	v_add_f32_e32 v247, v247, v251
	v_mul_f32_e32 v128, v24, v11
	v_mul_f32_e32 v129, v22, v11
	v_mul_f32_e32 v131, v21, v11
	v_mul_f32_e32 v130, v20, v11
	s_and_saveexec_b64 s[0:1], vcc
	ds_write_b32 v15, v244 offset:788
	ds_write_b32 v15, v245 offset:792
	ds_write_b32 v15, v246 offset:796
	ds_write_b32 v15, v247 offset:896
.LBB0_559:
	s_or_b64 exec, exec, s[0:1]
	v_mul_f32_e32 v240, v19, v11
	v_mul_f32_e32 v241, v17, v11
	v_mul_f32_e32 v242, v14, v11
	v_mul_f32_e32 v243, v13, v11
	v_mov_b32_dpp v244, v240 quad_perm:[1,0,3,2] row_mask:0xf bank_mask:0xf
	v_mov_b32_dpp v245, v241 quad_perm:[1,0,3,2] row_mask:0xf bank_mask:0xf
	v_mov_b32_dpp v246, v242 quad_perm:[1,0,3,2] row_mask:0xf bank_mask:0xf
	v_mov_b32_dpp v247, v243 quad_perm:[1,0,3,2] row_mask:0xf bank_mask:0xf
	v_fmac_f32_e32 v244, v19, v11
	v_fmac_f32_e32 v245, v17, v11
	v_fmac_f32_e32 v246, v14, v11
	v_fmac_f32_e32 v247, v13, v11
	v_mov_b32_dpp v248, v244 quad_perm:[2,3,0,1] row_mask:0xf bank_mask:0xf
	v_mov_b32_dpp v249, v245 quad_perm:[2,3,0,1] row_mask:0xf bank_mask:0xf
	v_mov_b32_dpp v250, v246 quad_perm:[2,3,0,1] row_mask:0xf bank_mask:0xf
	v_mov_b32_dpp v251, v247 quad_perm:[2,3,0,1] row_mask:0xf bank_mask:0xf
	v_add_f32_e32 v244, v244, v248
	v_add_f32_e32 v245, v245, v249
	v_add_f32_e32 v246, v246, v250
	v_add_f32_e32 v247, v247, v251
	v_mul_f32_e32 v132, v19, v11
	v_mul_f32_e32 v133, v17, v11
	v_mul_f32_e32 v134, v14, v11
	v_mul_f32_e32 v14, v13, v11
	s_and_saveexec_b64 s[0:1], vcc
	ds_write_b32 v15, v244 offset:900
	ds_write_b32 v15, v245 offset:904
	ds_write_b32 v15, v246 offset:908
	ds_write_b32 v15, v247 offset:912
